# SSD and DeltaNet scan chunk cumsum via DPP wave scan instead of 6 dependent ds_bpermute steps
# baseline (speedup 1.0000x reference)
; __device__ __forceinline__ unsigned short f2bf(float f) { unsigned u = __float_as_uint(f); u += 0x7FFFu + ((u >> 16) & 1u); return (unsigned short)(u >> 16); }
; __device__ __forceinline__ unsigned pack2bf(float lo, float hi) { unsigned r; asm("v_cvt_pk_bf16_f32 %0, %1, %2" : "=v"(r) : "v"(lo), "v"(hi)); return r; }
; __device__ void ssd_item(unsigned char* smem, const float* SCg, const float* SBg, const float* SXg, const float* STg, float* SYg, int b, int hd, int dir, bool store_ctx) {
;     ...
;   for (int c = 0; c < NCH; ++c) {
;     float cum = rda;
; #pragma unroll
;     for (int off = 1; off < 64; off <<= 1) { const float t = __shfl_up(cum, off); if (lane >= off) cum += t; }
;     const float cl = __shfl(cum, 63);
;     const float dtl = rdt;
; #pragma unroll
;     for (int i = 0; i < 4; ++i) {
;       const int id = tid + 512 * i, j = (id >> 3) & 63, c4 = (id & 7) + 8 * (id >> 9);
;       u32x2 w; w.x = pack2bf(rc[i][0], rc[i][1]); w.y = pack2bf(rc[i][2], rc[i][3]); *(u32x2*)(Cb + j * LDK + c4 * 4) = w;
;       w.x = pack2bf(rb[i][0], rb[i][1]); w.y = pack2bf(rb[i][2], rb[i][3]); *(u32x2*)(Bb + j * LDK + c4 * 4) = w;
; #pragma unroll
;       for (int q = 0; q < 4; ++q) BTb[(c4 * 4 + q) * LDJ + j] = f2bf(rb[i][q]);
;     }
; #pragma unroll
;     for (int i = 0; i < 2; ++i) {
;       const int id = tid + 512 * i, j = (id >> 3) & 63, c4 = (id & 7) + 8 * (id >> 9);
;       const float wj = __shfl(dtl, j) * __expf(cl - __shfl(cum, j));
; #pragma unroll
;       for (int q = 0; q < 4; ++q) { XTb[(c4 * 4 + q) * LDJ + j] = f2bf(rx[i][q]); XWb[(c4 * 4 + q) * LDJ + j] = f2bf(rx[i][q] * wj); }
;     }
.LBB0_314:
	s_waitcnt vmcnt(0)
	v_cvt_pk_bf16_f32 v58, v4, v5
	v_cvt_pk_bf16_f32 v59, v6, v7
	s_cmpk_eq_i32 s48, 0x8c0
	v_mov_b32_e32 v69, v100
	s_nop 1
	v_add_f32_dpp v69, v69, v69 row_shr:1 row_mask:0xf bank_mask:0xf
	s_nop 1
	v_add_f32_dpp v69, v69, v69 row_shr:2 row_mask:0xf bank_mask:0xf
	s_nop 1
	v_add_f32_dpp v69, v69, v69 row_shr:4 row_mask:0xf bank_mask:0xf
	s_nop 1
	v_add_f32_dpp v69, v69, v69 row_shr:8 row_mask:0xf bank_mask:0xf
	s_nop 1
	v_add_f32_dpp v69, v69, v69 row_bcast:15 row_mask:0xa bank_mask:0xf
	s_nop 1
	v_add_f32_dpp v69, v69, v69 row_bcast:31 row_mask:0xc bank_mask:0xf
	s_nop 1
	v_cvt_pk_bf16_f32 v56, v0, v1
	v_cvt_pk_bf16_f32 v57, v2, v3
	ds_write2st64_b64 v108, v[56:57], v[58:59] offset1:34
	v_bfe_u32 v56, v4, 16, 1
	v_add3_u32 v56, v4, v56, s65
	ds_write_b16_d16_hi v152, v56 offset:52224
	v_bfe_u32 v56, v5, 16, 1
	v_add3_u32 v56, v5, v56, s65
	ds_write_b16_d16_hi v153, v56 offset:52224
	v_bfe_u32 v56, v6, 16, 1
	v_add3_u32 v56, v6, v56, s65
	ds_write_b16_d16_hi v153, v56 offset:52368
	v_bfe_u32 v56, v7, 16, 1
	v_add3_u32 v56, v7, v56, s65
	ds_write_b16_d16_hi v153, v56 offset:52512
	v_cvt_pk_bf16_f32 v56, v8, v9
	v_cvt_pk_bf16_f32 v57, v10, v11
	v_cvt_pk_bf16_f32 v58, v12, v13
	v_cvt_pk_bf16_f32 v59, v14, v15
	ds_write2st64_b64 v109, v[56:57], v[58:59] offset1:34
	v_bfe_u32 v56, v12, 16, 1
	v_add3_u32 v56, v12, v56, s65
	ds_write_b16_d16_hi v154, v56 offset:52224
	v_bfe_u32 v56, v13, 16, 1
	v_add3_u32 v56, v13, v56, s65
	ds_write_b16_d16_hi v155, v56 offset:52224
	v_bfe_u32 v56, v14, 16, 1
	v_add3_u32 v56, v14, v56, s65
	ds_write_b16_d16_hi v155, v56 offset:52368
	v_bfe_u32 v56, v15, 16, 1
	v_add3_u32 v56, v15, v56, s65
	ds_write_b16_d16_hi v155, v56 offset:52512
	v_cvt_pk_bf16_f32 v56, v16, v17
	v_cvt_pk_bf16_f32 v57, v18, v19
	v_cvt_pk_bf16_f32 v58, v20, v21
	v_cvt_pk_bf16_f32 v59, v22, v23
	ds_write2st64_b64 v110, v[56:57], v[58:59] offset1:34
	v_bfe_u32 v56, v20, 16, 1
	v_add3_u32 v56, v20, v56, s65
	ds_write_b16_d16_hi v156, v56 offset:52224
	v_bfe_u32 v56, v21, 16, 1
	v_add3_u32 v56, v21, v56, s65
	ds_write_b16_d16_hi v156, v56 offset:52368
	v_bfe_u32 v56, v22, 16, 1
	v_add3_u32 v56, v22, v56, s65
	ds_write_b16_d16_hi v156, v56 offset:52512
	v_bfe_u32 v56, v23, 16, 1
	v_add3_u32 v56, v23, v56, s65
	ds_write_b16_d16_hi v156, v56 offset:52656
	v_cvt_pk_bf16_f32 v56, v24, v25
	v_cvt_pk_bf16_f32 v57, v26, v27
	v_cvt_pk_bf16_f32 v58, v28, v29
	v_cvt_pk_bf16_f32 v59, v30, v31
	ds_write2st64_b64 v111, v[56:57], v[58:59] offset1:34
	v_bfe_u32 v56, v28, 16, 1
	v_add3_u32 v56, v28, v56, s65
	ds_bpermute_b32 v171, v235, v69
	ds_write_b16_d16_hi v157, v56 offset:52224
	v_bfe_u32 v56, v29, 16, 1
	ds_bpermute_b32 v57, v96, v69
	v_add3_u32 v56, v29, v56, s65
	ds_write_b16_d16_hi v157, v56 offset:52368
	v_bfe_u32 v56, v30, 16, 1
	v_add3_u32 v56, v30, v56, s65
	ds_write_b16_d16_hi v157, v56 offset:52512
	v_bfe_u32 v56, v31, 16, 1
	v_add3_u32 v56, v31, v56, s65
	s_waitcnt lgkmcnt(2)
	v_sub_f32_e32 v57, v171, v57
	ds_write_b16_d16_hi v157, v56 offset:52656
	ds_bpermute_b32 v56, v96, v68
	v_mul_f32_e32 v57, 0x3fb8aa3b, v57
	v_exp_f32_e32 v57, v57
	s_waitcnt lgkmcnt(0)
	v_mul_f32_e32 v56, v57, v56
	v_bfe_u32 v57, v32, 16, 1
	v_add3_u32 v57, v32, v57, s65
	ds_write_b16_d16_hi v112, v57
	v_mul_f32_e32 v57, v32, v56
	v_bfe_u32 v58, v57, 16, 1
	v_add3_u32 v57, v57, v58, s65
	ds_write_b16_d16_hi v113, v57
	v_bfe_u32 v57, v33, 16, 1
	v_add3_u32 v57, v33, v57, s65
	ds_write_b16_d16_hi v114, v57
	v_mul_f32_e32 v57, v33, v56
	v_bfe_u32 v58, v57, 16, 1
	v_add3_u32 v57, v57, v58, s65
	ds_write_b16_d16_hi v115, v57
	v_bfe_u32 v57, v34, 16, 1
	v_add3_u32 v57, v34, v57, s65
	ds_write_b16_d16_hi v116, v57
	v_mul_f32_e32 v57, v34, v56
	v_bfe_u32 v58, v57, 16, 1
	v_add3_u32 v57, v57, v58, s65
	ds_write_b16_d16_hi v117, v57
	v_bfe_u32 v57, v35, 16, 1
	v_add3_u32 v57, v35, v57, s65
	ds_write_b16_d16_hi v118, v57
	v_mul_f32_e32 v57, v35, v56
	v_bfe_u32 v58, v57, 16, 1
	v_add3_u32 v57, v57, v58, s65
	ds_write_b16_d16_hi v119, v57
	v_bfe_u32 v57, v36, 16, 1
	v_add3_u32 v57, v36, v57, s65
	ds_write_b16_d16_hi v120, v57
	v_mul_f32_e32 v57, v36, v56
	v_bfe_u32 v58, v57, 16, 1
	v_add3_u32 v57, v57, v58, s65
	ds_write_b16_d16_hi v121, v57
	v_bfe_u32 v57, v37, 16, 1
	v_add3_u32 v57, v37, v57, s65
	ds_write_b16_d16_hi v122, v57
	v_mul_f32_e32 v57, v37, v56
	v_bfe_u32 v58, v57, 16, 1
	v_add3_u32 v57, v57, v58, s65
	ds_write_b16_d16_hi v123, v57
	v_bfe_u32 v57, v38, 16, 1
	v_add3_u32 v57, v38, v57, s65
	ds_write_b16_d16_hi v124, v57
	v_mul_f32_e32 v57, v38, v56
	v_bfe_u32 v58, v57, 16, 1
	v_add3_u32 v57, v57, v58, s65
	ds_write_b16_d16_hi v125, v57
	v_bfe_u32 v57, v39, 16, 1
	v_add3_u32 v57, v39, v57, s65
	v_mul_f32_e32 v56, v39, v56
	ds_write_b16_d16_hi v126, v57
	v_bfe_u32 v57, v56, 16, 1
	v_add3_u32 v56, v56, v57, s65
	ds_write_b16_d16_hi v127, v56
	s_waitcnt lgkmcnt(0)
	s_barrier
	s_cbranch_scc1 .LBB0_316
	s_cmp_lt_u32 s49, 3
	s_cselect_b64 vcc, -1, 0
	s_and_b64 s[44:45], vcc, exec
	s_movk_i32 s3, 0x8ff
	v_add_u32_e32 v0, s48, v95
	s_cselect_b32 s3, 0xff, s3
	v_add_u32_e32 v56, s48, v94
	v_add_u32_e32 v1, 64, v0
	v_add_u32_e32 v0, 0xffffff40, v0
	s_cselect_b32 s33, s47, s40
	s_add_i32 s3, s46, s3
	v_add_u32_e32 v57, 64, v56
	v_add_u32_e32 v56, 0xffffff40, v56
	v_cndmask_b32_e32 v0, v0, v1, vcc
	v_add_u32_e32 v1, s3, v151
	v_cndmask_b32_e32 v56, v56, v57, vcc
	v_add_u32_e32 v57, s3, v150
	v_cndmask_b32_e64 v0, v1, v0, s[38:39]
	v_cndmask_b32_e64 v56, v57, v56, s[38:39]
	v_add_u32_e32 v32, s33, v0
	v_add_u32_e32 v56, s33, v56
	v_ashrrev_i32_e32 v33, 31, v32
	v_ashrrev_i32_e32 v57, 31, v56
	v_lshlrev_b64 v[24:25], 10, v[32:33]
	v_lshlrev_b64 v[32:33], 11, v[32:33]
	v_lshlrev_b64 v[56:57], 7, v[56:57]
	v_lshl_add_u64 v[0:1], v[72:73], 0, v[24:25]
	v_lshl_add_u64 v[4:5], v[74:75], 0, v[24:25]
	v_lshl_add_u64 v[8:9], v[76:77], 0, v[24:25]
	v_lshl_add_u64 v[12:13], v[78:79], 0, v[24:25]
	v_lshl_add_u64 v[16:17], v[80:81], 0, v[24:25]
	v_lshl_add_u64 v[20:21], v[82:83], 0, v[24:25]
	v_lshl_add_u64 v[26:27], v[84:85], 0, v[24:25]
	v_lshl_add_u64 v[28:29], v[86:87], 0, v[24:25]
	v_lshl_add_u64 v[34:35], v[88:89], 0, v[32:33]
	v_lshl_add_u64 v[36:37], v[90:91], 0, v[32:33]
	v_lshl_add_u64 v[56:57], s[42:43], 0, v[56:57]
	global_load_dwordx4 v[0:3], v[0:1], off
	s_nop 0
	global_load_dwordx4 v[4:7], v[4:5], off
	s_nop 0
	global_load_dwordx4 v[8:11], v[8:9], off
	s_nop 0
	global_load_dwordx4 v[12:15], v[12:13], off
	s_nop 0
	global_load_dwordx4 v[16:19], v[16:17], off
	s_nop 0
	global_load_dwordx4 v[20:23], v[20:21], off
	s_nop 0
	global_load_dwordx4 v[24:27], v[26:27], off
	s_nop 0
	global_load_dwordx4 v[28:31], v[28:29], off
	s_nop 0
	global_load_dwordx4 v[32:35], v[34:35], off
	s_nop 0
	global_load_dwordx4 v[36:39], v[36:37], off
	s_nop 0
	global_load_dword v170, v[56:57], off
	global_load_dword v100, v[56:57], off offset:64

; __device__ __forceinline__ unsigned pack2bf(float lo, float hi) { unsigned r; asm("v_cvt_pk_bf16_f32 %0, %1, %2" : "=v"(r) : "v"(lo), "v"(hi)); return r; }
; __device__ void dn_scan_item(unsigned char* smem, const float* Qg, const float* Kg, const float* Vg, const float* BGg, const unsigned char* imgs  , unsigned* counter,
;                              float* Og, int b, int h, int dir, int vh, bool store_ctx) {
;     ...
;   for (int c = 0; c < NCH; ++c) {
;     float cum = rgam;
; #pragma unroll
;     for (int off = 1; off < 64; off <<= 1) { const float t = __shfl_up(cum, off); if (lane >= off) cum += t; }
;     const float cl = __shfl(cum, 63);
;     const float betl = rbeta;
;     float* wl = (float*)(KdT + 64 * LDJ) + wid * 192;
;     wl[lane] = __expf(cum); wl[64 + lane] = betl; wl[128 + lane] = __expf(cl - cum);
; #pragma unroll
;     for (int i = 0; i < 4; ++i) {
;       const int id = tid + 512 * i, j = (id >> 3) & 63, c4 = (id & 7) + 8 * (id >> 9);
;       u32x2 w; w.x = pack2bf(rq[i][0], rq[i][1]); w.y = pack2bf(rq[i][2], rq[i][3]); *(u32x2*)(Qb + j * LDK + c4 * 4) = w;
;       w.x = pack2bf(rk[i][0], rk[i][1]); w.y = pack2bf(rk[i][2], rk[i][3]); *(u32x2*)(Kb + j * LDK + c4 * 4) = w;
;     }
; #pragma unroll
;     for (int i = 0; i < 2; ++i) {
;       const int id = tid + 512 * i, j = id >> 4, c4 = id & 15;
;       u32x2 w; w.x = pack2bf(rv[i][0], rv[i][1]); w.y = pack2bf(rv[i][2], rv[i][3]); *(u32x2*)(Vb + j * LDJ + c4 * 4) = w;
;     }
; #pragma unroll
;     for (int i = 0; i < 3; ++i) {
;       const int o = tid + 512 * i;
;       if (o < 2 * (DN_IMG / 16)) { const int which = o / (DN_IMG / 16), oo = o % (DN_IMG / 16); *(u32x4*)((unsigned char*)(which ? QKb : Tb) + oo * 16) = ri[i]; }
.LBB0_385:
	s_waitcnt vmcnt(0)
	v_mov_b32_e32 v68, v169
	v_cvt_pk_bf16_f32 v52, v52, v53
	v_cvt_pk_bf16_f32 v53, v54, v55
	v_cvt_pk_bf16_f32 v44, v44, v45
	v_cvt_pk_bf16_f32 v45, v46, v47
	s_nop 1
	v_add_f32_dpp v68, v68, v68 row_shr:1 row_mask:0xf bank_mask:0xf
	v_cvt_pk_bf16_f32 v36, v36, v37
	v_cvt_pk_bf16_f32 v37, v38, v39
	v_cvt_pk_bf16_f32 v24, v24, v25
	v_cvt_pk_bf16_f32 v25, v26, v27
	s_nop 1
	v_add_f32_dpp v68, v68, v68 row_shr:2 row_mask:0xf bank_mask:0xf
	v_cvt_pk_bf16_f32 v32, v32, v33
	v_cvt_pk_bf16_f32 v33, v34, v35
	v_cvt_pk_bf16_f32 v60, v60, v61
	v_cvt_pk_bf16_f32 v61, v62, v63
	s_nop 1
	v_add_f32_dpp v68, v68, v68 row_shr:4 row_mask:0xf bank_mask:0xf
	v_cvt_pk_bf16_f32 v48, v48, v49
	v_cvt_pk_bf16_f32 v49, v50, v51
	v_cvt_pk_bf16_f32 v40, v40, v41
	v_cvt_pk_bf16_f32 v41, v42, v43
	s_nop 1
	v_add_f32_dpp v68, v68, v68 row_shr:8 row_mask:0xf bank_mask:0xf
	v_cvt_pk_bf16_f32 v27, v58, v59
	s_nop 1
	v_add_f32_dpp v68, v68, v68 row_bcast:15 row_mask:0xa bank_mask:0xf
	s_nop 1
	v_add_f32_dpp v68, v68, v68 row_bcast:31 row_mask:0xc bank_mask:0xf
	s_nop 1
	v_mov_b32_e32 v34, v68
	ds_bpermute_b32 v172, v235, v34
	v_mul_f32_e32 v35, 0x3fb8aa3b, v34
	v_exp_f32_e32 v38, v35
	v_cvt_pk_bf16_f32 v26, v56, v57
	v_cvt_pk_bf16_f32 v35, v66, v67
	s_waitcnt lgkmcnt(0)
	v_sub_f32_e32 v34, v172, v34
	v_mul_f32_e32 v34, 0x3fb8aa3b, v34
	v_exp_f32_e32 v39, v34
	v_cvt_pk_bf16_f32 v34, v64, v65
	ds_write2st64_b32 v139, v38, v151 offset0:240 offset1:241
	ds_write_b32 v139, v39 offset:61952
	ds_write2st64_b64 v141, v[60:61], v[52:53] offset1:34
	ds_write2st64_b64 v142, v[48:49], v[44:45] offset1:34
	ds_write2st64_b64 v143, v[40:41], v[36:37] offset1:34
	ds_write2st64_b64 v144, v[32:33], v[24:25] offset1:34
	ds_write_b64 v159, v[26:27]
	ds_write_b64 v158, v[34:35]
	s_and_saveexec_b64 s[24:25], s[4:5]
	s_cbranch_execz .LBB0_397
	v_add_u32_e32 v24, v145, v148
	ds_write_b128 v24, v[16:19]
	s_or_b64 exec, exec, s[24:25]
	s_and_saveexec_b64 s[24:25], s[6:7]
	s_cbranch_execnz .LBB0_398
